# attention tile loop: one static priority for the raised wave group (three in-loop conditional raise/drop diamonds removed), dropped at loop exit
# speedup vs baseline: 1.0010x; 1.0010x over previous
.LBB0_594:
	s_add_i32 s42, s4, 1
	s_cmp_lt_i32 s42, s58
	s_cselect_b32 s4, s42, s4
	s_xor_b32 s43, s61, 0x10000
	s_lshl_b64 s[48:49], s[4:5], 17
	s_add_i32 s43, s59, s43
	v_lshl_add_u64 v[14:15], v[194:195], 0, s[48:49]
	s_mov_b32 m0, s43
	v_lshl_add_u64 v[16:17], v[14:15], 0, s[28:29]
	global_load_lds_dwordx4 v[14:15], off
	s_add_i32 m0, s43, 0x2000
	s_and_b64 vcc, exec, s[0:1]
	global_load_lds_dwordx4 v[16:17], off
	v_lshl_add_u64 v[16:17], v[14:15], 0, s[30:31]
	s_add_i32 m0, s43, 0x4000
	v_lshl_add_u64 v[14:15], v[14:15], 0, s[34:35]
	global_load_lds_dwordx4 v[16:17], off
	s_add_i32 m0, s43, 0x6000
	s_nop 0
	global_load_lds_dwordx4 v[14:15], off
.LBB0_596:
	v_or_b32_e32 v14, s61, v210
	v_add_u32_e32 v223, v209, v14
	v_exp_f32_e32 v17, v150
	v_exp_f32_e32 v212, v151
	v_exp_f32_e32 v213, v152
	v_exp_f32_e32 v214, v153
	s_waitcnt lgkmcnt(0)
	s_barrier
	ds_read_b128 v[150:153], v223 offset:32768
	v_exp_f32_e32 v2, v146
	v_exp_f32_e32 v4, v147
	v_exp_f32_e32 v15, v148
	v_exp_f32_e32 v16, v149
	v_xad_u32 v248, v14, 32, v209
	v_cvt_pk_bf16_f32 v146, v2, v4
	v_cvt_pk_bf16_f32 v148, v17, v212
	v_cvt_pk_bf16_f32 v147, v15, v16
	v_cvt_pk_bf16_f32 v149, v213, v214
	v_exp_f32_e32 v215, v154
	v_exp_f32_e32 v216, v155
	v_exp_f32_e32 v217, v156
	v_exp_f32_e32 v218, v157
	ds_read_b128 v[154:157], v248 offset:32768
	ds_read_b128 v[224:227], v223 offset:36864
	ds_read_b128 v[228:231], v248 offset:36864
	ds_read_b128 v[232:235], v223 offset:40960
	ds_read_b128 v[236:239], v248 offset:40960
	ds_read_b128 v[240:243], v223 offset:45056
	ds_read_b128 v[244:247], v248 offset:45056
	s_waitcnt lgkmcnt(0)
	v_mfma_f32_32x32x16_bf16 v[130:145], v[150:153], v[146:149], v[130:145]
	v_exp_f32_e32 v219, v158
	v_exp_f32_e32 v220, v159
	v_exp_f32_e32 v221, v160
	v_exp_f32_e32 v222, v161
	v_cvt_pk_bf16_f32 v150, v215, v216
	v_cvt_pk_bf16_f32 v151, v217, v218
	v_cvt_pk_bf16_f32 v152, v219, v220
	v_cvt_pk_bf16_f32 v153, v221, v222
	ds_read_b128 v[158:161], v223 offset:49152
	s_lshl_b64 s[48:49], s[4:5], 7
	v_mfma_f32_32x32x16_bf16 v[130:145], v[154:157], v[150:153], v[130:145]
	ds_read_b128 v[154:157], v248 offset:49152
	s_add_i32 m0, s43, 0x8000
	s_and_b64 vcc, exec, s[0:1]
	v_mfma_f32_32x32x16_bf16 v[114:129], v[224:227], v[146:149], v[114:129]
	ds_read_b128 v[224:227], v223 offset:53248
	v_mfma_f32_32x32x16_bf16 v[114:129], v[228:231], v[150:153], v[114:129]
	ds_read_b128 v[228:231], v248 offset:53248
	v_mfma_f32_32x32x16_bf16 v[98:113], v[232:235], v[146:149], v[98:113]
	ds_read_b128 v[232:235], v223 offset:57344
	v_mfma_f32_32x32x16_bf16 v[98:113], v[236:239], v[150:153], v[98:113]
	ds_read_b128 v[236:239], v248 offset:57344
	v_mfma_f32_32x32x16_bf16 v[82:97], v[240:243], v[146:149], v[82:97]
	ds_read_b128 v[240:243], v223 offset:61440
	v_mfma_f32_32x32x16_bf16 v[82:97], v[244:247], v[150:153], v[82:97]
	ds_read_b128 v[244:247], v248 offset:61440
	s_waitcnt lgkmcnt(0)
	v_mfma_f32_32x32x16_bf16 v[66:81], v[158:161], v[146:149], v[66:81]
	v_mfma_f32_32x32x16_bf16 v[66:81], v[154:157], v[150:153], v[66:81]
	v_lshl_add_u64 v[154:155], v[192:193], 0, s[48:49]
	global_load_lds_dwordx4 v[154:155], off
	v_lshl_add_u64 v[154:155], v[154:155], 0, s[38:39]
	s_add_i32 m0, s43, 0xa000
	s_nop 0
	global_load_lds_dwordx4 v[154:155], off
	v_lshl_add_u64 v[154:155], v[154:155], 0, s[38:39]
	s_add_i32 m0, s43, 0xc000
	v_mfma_f32_32x32x16_bf16 v[50:65], v[224:227], v[146:149], v[50:65]
	global_load_lds_dwordx4 v[154:155], off
	s_add_i32 m0, s43, 0xe000
	v_mfma_f32_32x32x16_bf16 v[34:49], v[232:235], v[146:149], v[34:49]
	v_mfma_f32_32x32x16_bf16 v[18:33], v[240:243], v[146:149], v[18:33]
	v_lshl_add_u64 v[146:147], v[154:155], 0, s[38:39]
	global_load_lds_dwordx4 v[146:147], off
	s_waitcnt lgkmcnt(0)
	s_barrier
	v_mfma_f32_32x32x16_bf16 v[50:65], v[228:231], v[150:153], v[50:65]
	v_mfma_f32_32x32x16_bf16 v[34:49], v[236:239], v[150:153], v[34:49]
	v_mfma_f32_32x32x16_bf16 v[18:33], v[244:247], v[150:153], v[18:33]
.LBB0_598:
	ds_read_b128 v[224:227], v6 offset:16384
	v_xor_b32_e32 v146, 0x80000000, v5
	ds_read_b128 v[228:231], v7 offset:16384
	v_mov_b32_e32 v147, v146
	v_mov_b32_e32 v148, v146
	v_mov_b32_e32 v149, v146
	v_mov_b32_e32 v150, v146
	v_mov_b32_e32 v151, v146
	v_mov_b32_e32 v152, v146
	v_mov_b32_e32 v153, v146
	v_mov_b32_e32 v154, v146
	v_mov_b32_e32 v155, v146
	v_mov_b32_e32 v156, v146
	v_mov_b32_e32 v157, v146
	v_mov_b32_e32 v158, v146
	v_mov_b32_e32 v159, v146
	v_mov_b32_e32 v160, v146
	v_mov_b32_e32 v161, v146
	ds_read_b128 v[232:235], v8 offset:16384
	ds_read_b128 v[6:9], v9 offset:16384
	ds_read_b128 v[236:239], v10 offset:16384
	ds_read_b128 v[240:243], v11 offset:16384
	s_waitcnt lgkmcnt(0)
	v_mfma_f32_32x32x16_bf16 v[146:161], v[224:227], v[162:165], v[146:161]
	ds_read_b128 v[224:227], v12 offset:16384
	v_add_f32_e32 v2, v2, v4
	v_add_f32_e32 v4, v16, v15
	v_add_f32_e32 v2, 0, v2
	v_add_f32_e32 v15, v212, v17
	v_add_f32_e32 v2, v4, v2
	v_add_f32_e32 v16, v214, v213
	v_mfma_f32_32x32x16_bf16 v[146:161], v[228:231], v[166:169], v[146:161]
	ds_read_b128 v[10:13], v13 offset:16384
	v_add_f32_e32 v2, v15, v2
	v_add_f32_e32 v17, v216, v215
	v_add_f32_e32 v2, v16, v2
	v_add_f32_e32 v212, v218, v217
	v_add_f32_e32 v2, v17, v2
	v_add_f32_e32 v213, v220, v219
	v_mfma_f32_32x32x16_bf16 v[146:161], v[232:235], v[170:173], v[146:161]
	ds_read_b128 v[228:231], v206
	v_add_f32_e32 v2, v212, v2
	v_add_f32_e32 v214, v221, v222
	v_add_f32_e32 v2, v213, v2
	v_add_f32_e32 v2, v214, v2
	v_mfma_f32_32x32x16_bf16 v[146:161], v[6:9], v[174:177], v[146:161]
	ds_read_b128 v[6:9], v206 offset:8192
	v_mfma_f32_32x32x16_bf16 v[146:161], v[236:239], v[178:181], v[146:161]
	v_mfma_f32_32x32x16_bf16 v[146:161], v[240:243], v[182:185], v[146:161]
	s_waitcnt lgkmcnt(0)
	v_mfma_f32_32x32x16_bf16 v[146:161], v[224:227], v[228:231], v[146:161]
	v_mfma_f32_32x32x16_bf16 v[146:161], v[10:13], v[6:9], v[146:161]
	v_add_f32_e32 v6, v211, v2
	s_nop 10
	v_max_f32_e32 v2, v147, v147
	v_max_f32_e32 v4, v146, v146
	v_max_f32_e32 v2, v4, v2
	v_max3_f32 v2, v2, v148, v149
	v_max3_f32 v2, v2, v150, v151
	v_max3_f32 v2, v2, v152, v153
	v_max3_f32 v2, v2, v154, v155
	v_max3_f32 v2, v2, v156, v157
	v_max3_f32 v2, v2, v158, v159
	v_max3_f32 v2, v2, v160, v161
	v_mov_b32_e32 v4, v2
	s_nop 1
	v_permlane32_swap_b32_e32 v2, v4
	v_cmp_lt_f32_e32 vcc, s84, v2
	s_cbranch_vccz .LBB0_600
	v_max_f32_e32 v2, v2, v2
	v_max_f32_e32 v2, 0, v2
	v_exp_f32_e64 v4, -v2
	v_pk_add_f32 v[146:147], v[146:147], v[2:3] op_sel_hi:[1,0] neg_lo:[0,1] neg_hi:[0,1]
	v_pk_add_f32 v[148:149], v[148:149], v[2:3] op_sel_hi:[1,0] neg_lo:[0,1] neg_hi:[0,1]
	v_pk_add_f32 v[150:151], v[150:151], v[2:3] op_sel_hi:[1,0] neg_lo:[0,1] neg_hi:[0,1]
	v_mul_f32_e32 v6, v6, v4
	v_pk_mul_f32 v[32:33], v[32:33], v[4:5] op_sel_hi:[1,0]
	v_pk_mul_f32 v[30:31], v[30:31], v[4:5] op_sel_hi:[1,0]
	v_pk_mul_f32 v[28:29], v[28:29], v[4:5] op_sel_hi:[1,0]
	v_pk_mul_f32 v[26:27], v[26:27], v[4:5] op_sel_hi:[1,0]
	v_pk_mul_f32 v[24:25], v[24:25], v[4:5] op_sel_hi:[1,0]
	v_pk_mul_f32 v[22:23], v[22:23], v[4:5] op_sel_hi:[1,0]
	v_pk_mul_f32 v[20:21], v[20:21], v[4:5] op_sel_hi:[1,0]
	v_pk_mul_f32 v[18:19], v[18:19], v[4:5] op_sel_hi:[1,0]
	v_pk_mul_f32 v[48:49], v[48:49], v[4:5] op_sel_hi:[1,0]
	v_pk_mul_f32 v[46:47], v[46:47], v[4:5] op_sel_hi:[1,0]
	v_pk_mul_f32 v[44:45], v[44:45], v[4:5] op_sel_hi:[1,0]
	v_pk_mul_f32 v[42:43], v[42:43], v[4:5] op_sel_hi:[1,0]
	v_pk_mul_f32 v[40:41], v[40:41], v[4:5] op_sel_hi:[1,0]
	v_pk_mul_f32 v[38:39], v[38:39], v[4:5] op_sel_hi:[1,0]
	v_pk_mul_f32 v[36:37], v[36:37], v[4:5] op_sel_hi:[1,0]
	v_pk_mul_f32 v[34:35], v[34:35], v[4:5] op_sel_hi:[1,0]
	v_pk_mul_f32 v[64:65], v[64:65], v[4:5] op_sel_hi:[1,0]
	v_pk_mul_f32 v[62:63], v[62:63], v[4:5] op_sel_hi:[1,0]
	v_pk_mul_f32 v[60:61], v[60:61], v[4:5] op_sel_hi:[1,0]
	v_pk_mul_f32 v[58:59], v[58:59], v[4:5] op_sel_hi:[1,0]
	v_pk_mul_f32 v[56:57], v[56:57], v[4:5] op_sel_hi:[1,0]
	v_pk_mul_f32 v[54:55], v[54:55], v[4:5] op_sel_hi:[1,0]
	v_pk_mul_f32 v[52:53], v[52:53], v[4:5] op_sel_hi:[1,0]
	v_pk_mul_f32 v[50:51], v[50:51], v[4:5] op_sel_hi:[1,0]
	v_pk_mul_f32 v[80:81], v[80:81], v[4:5] op_sel_hi:[1,0]
	v_pk_mul_f32 v[78:79], v[78:79], v[4:5] op_sel_hi:[1,0]
	v_pk_mul_f32 v[76:77], v[76:77], v[4:5] op_sel_hi:[1,0]
	v_pk_mul_f32 v[74:75], v[74:75], v[4:5] op_sel_hi:[1,0]
	v_pk_mul_f32 v[72:73], v[72:73], v[4:5] op_sel_hi:[1,0]
	v_pk_mul_f32 v[70:71], v[70:71], v[4:5] op_sel_hi:[1,0]
	v_pk_mul_f32 v[68:69], v[68:69], v[4:5] op_sel_hi:[1,0]
	v_pk_mul_f32 v[66:67], v[66:67], v[4:5] op_sel_hi:[1,0]
	v_pk_mul_f32 v[96:97], v[96:97], v[4:5] op_sel_hi:[1,0]
	v_pk_mul_f32 v[94:95], v[94:95], v[4:5] op_sel_hi:[1,0]
	v_pk_mul_f32 v[92:93], v[92:93], v[4:5] op_sel_hi:[1,0]
	v_pk_mul_f32 v[90:91], v[90:91], v[4:5] op_sel_hi:[1,0]
	v_pk_mul_f32 v[88:89], v[88:89], v[4:5] op_sel_hi:[1,0]
	v_pk_mul_f32 v[86:87], v[86:87], v[4:5] op_sel_hi:[1,0]
	v_pk_mul_f32 v[84:85], v[84:85], v[4:5] op_sel_hi:[1,0]
	v_pk_mul_f32 v[82:83], v[82:83], v[4:5] op_sel_hi:[1,0]
	v_pk_mul_f32 v[112:113], v[112:113], v[4:5] op_sel_hi:[1,0]
	v_pk_mul_f32 v[110:111], v[110:111], v[4:5] op_sel_hi:[1,0]
	v_pk_mul_f32 v[108:109], v[108:109], v[4:5] op_sel_hi:[1,0]
	v_pk_mul_f32 v[106:107], v[106:107], v[4:5] op_sel_hi:[1,0]
	v_pk_mul_f32 v[104:105], v[104:105], v[4:5] op_sel_hi:[1,0]
	v_pk_mul_f32 v[102:103], v[102:103], v[4:5] op_sel_hi:[1,0]
	v_pk_mul_f32 v[100:101], v[100:101], v[4:5] op_sel_hi:[1,0]
	v_pk_mul_f32 v[98:99], v[98:99], v[4:5] op_sel_hi:[1,0]
	v_pk_mul_f32 v[128:129], v[128:129], v[4:5] op_sel_hi:[1,0]
	v_pk_mul_f32 v[126:127], v[126:127], v[4:5] op_sel_hi:[1,0]
	v_pk_mul_f32 v[124:125], v[124:125], v[4:5] op_sel_hi:[1,0]
	v_pk_mul_f32 v[122:123], v[122:123], v[4:5] op_sel_hi:[1,0]
	v_pk_mul_f32 v[120:121], v[120:121], v[4:5] op_sel_hi:[1,0]
	v_pk_mul_f32 v[118:119], v[118:119], v[4:5] op_sel_hi:[1,0]
	v_pk_mul_f32 v[116:117], v[116:117], v[4:5] op_sel_hi:[1,0]
	v_pk_mul_f32 v[114:115], v[114:115], v[4:5] op_sel_hi:[1,0]
	v_pk_mul_f32 v[144:145], v[144:145], v[4:5] op_sel_hi:[1,0]
	v_pk_mul_f32 v[142:143], v[142:143], v[4:5] op_sel_hi:[1,0]
	v_pk_mul_f32 v[140:141], v[140:141], v[4:5] op_sel_hi:[1,0]
	v_pk_mul_f32 v[138:139], v[138:139], v[4:5] op_sel_hi:[1,0]
	v_pk_mul_f32 v[136:137], v[136:137], v[4:5] op_sel_hi:[1,0]
	v_pk_mul_f32 v[134:135], v[134:135], v[4:5] op_sel_hi:[1,0]
	v_pk_mul_f32 v[132:133], v[132:133], v[4:5] op_sel_hi:[1,0]
	v_pk_mul_f32 v[130:131], v[130:131], v[4:5] op_sel_hi:[1,0]
	v_pk_add_f32 v[152:153], v[152:153], v[2:3] op_sel_hi:[1,0] neg_lo:[0,1] neg_hi:[0,1]
	v_pk_add_f32 v[154:155], v[154:155], v[2:3] op_sel_hi:[1,0] neg_lo:[0,1] neg_hi:[0,1]
	v_pk_add_f32 v[156:157], v[156:157], v[2:3] op_sel_hi:[1,0] neg_lo:[0,1] neg_hi:[0,1]
	v_pk_add_f32 v[158:159], v[158:159], v[2:3] op_sel_hi:[1,0] neg_lo:[0,1] neg_hi:[0,1]
	v_pk_add_f32 v[160:161], v[160:161], v[2:3] op_sel_hi:[1,0] neg_lo:[0,1] neg_hi:[0,1]
	v_add_f32_e32 v5, v5, v2

.LBB0_602:
	s_waitcnt vmcnt(4)
	v_xad_u32 v236, v14, 64, v209
	v_exp_f32_e32 v2, v146
	v_exp_f32_e32 v4, v147
	v_exp_f32_e32 v7, v148
	v_exp_f32_e32 v16, v149
	s_waitcnt lgkmcnt(0)
	s_barrier
	ds_read_b128 v[146:149], v236 offset:32768
	v_exp_f32_e32 v17, v150
	v_exp_f32_e32 v211, v151
	v_exp_f32_e32 v228, v152
	v_exp_f32_e32 v229, v153
	v_xad_u32 v237, v14, s83, v209
	v_cvt_pk_bf16_f32 v8, v2, v4
	v_cvt_pk_bf16_f32 v9, v7, v16
	v_cvt_pk_bf16_f32 v10, v17, v211
	v_cvt_pk_bf16_f32 v11, v228, v229
	ds_read_b128 v[12:15], v237 offset:32768
	ds_read_b128 v[150:153], v236 offset:36864
	v_exp_f32_e32 v230, v154
	v_exp_f32_e32 v231, v155
	v_exp_f32_e32 v232, v156
	v_exp_f32_e32 v233, v157
	ds_read_b128 v[154:157], v237 offset:36864
	ds_read_b128 v[212:215], v236 offset:40960
	ds_read_b128 v[216:219], v237 offset:40960
	ds_read_b128 v[220:223], v236 offset:45056
	ds_read_b128 v[224:227], v237 offset:45056
	s_waitcnt lgkmcnt(0)
	v_mfma_f32_32x32x16_bf16 v[130:145], v[146:149], v[8:11], v[130:145]
	v_exp_f32_e32 v234, v158
	v_exp_f32_e32 v235, v159
	v_exp_f32_e32 v238, v160
	v_exp_f32_e32 v239, v161
	v_cvt_pk_bf16_f32 v146, v230, v231
	v_cvt_pk_bf16_f32 v147, v232, v233
	v_cvt_pk_bf16_f32 v148, v234, v235
	v_cvt_pk_bf16_f32 v149, v238, v239
	ds_read_b128 v[158:161], v236 offset:49152
	v_add_f32_e32 v2, v2, v4
	v_mfma_f32_32x32x16_bf16 v[130:145], v[12:15], v[146:149], v[130:145]
	ds_read_b128 v[12:15], v237 offset:49152
	v_add_f32_e32 v2, 0, v2
	v_add_f32_e32 v4, v16, v7
	v_add_f32_e32 v2, v4, v2
	v_add_f32_e32 v4, v211, v17
	v_add_f32_e32 v2, v4, v2
	v_add_f32_e32 v4, v229, v228
	v_mfma_f32_32x32x16_bf16 v[114:129], v[150:153], v[8:11], v[114:129]
	ds_read_b128 v[150:153], v236 offset:53248
	v_add_f32_e32 v2, v4, v2
	v_add_f32_e32 v4, v231, v230
	v_add_f32_e32 v2, v4, v2
	v_add_f32_e32 v4, v233, v232
	v_add_f32_e32 v2, v4, v2
	v_add_f32_e32 v4, v235, v234
	v_mfma_f32_32x32x16_bf16 v[114:129], v[154:157], v[146:149], v[114:129]
	ds_read_b128 v[154:157], v237 offset:53248
	v_add_f32_e32 v2, v4, v2
	v_add_f32_e32 v4, v238, v239
	v_add_f32_e32 v2, v4, v2
	s_add_i32 s60, s60, 0x10000
	v_add_f32_e32 v211, v6, v2
	s_cmp_eq_u32 s58, s42
	v_mfma_f32_32x32x16_bf16 v[98:113], v[212:215], v[8:11], v[98:113]
	ds_read_b128 v[212:215], v236 offset:57344
	v_mfma_f32_32x32x16_bf16 v[98:113], v[216:219], v[146:149], v[98:113]
	ds_read_b128 v[216:219], v237 offset:57344
	v_mfma_f32_32x32x16_bf16 v[82:97], v[220:223], v[8:11], v[82:97]
	ds_read_b128 v[220:223], v236 offset:61440
	v_mfma_f32_32x32x16_bf16 v[82:97], v[224:227], v[146:149], v[82:97]
	ds_read_b128 v[224:227], v237 offset:61440
	s_waitcnt vmcnt(0)
	s_waitcnt lgkmcnt(0)
	s_barrier
	s_waitcnt lgkmcnt(0)
	v_mfma_f32_32x32x16_bf16 v[66:81], v[158:161], v[8:11], v[66:81]
	v_mfma_f32_32x32x16_bf16 v[50:65], v[150:153], v[8:11], v[50:65]
	v_mfma_f32_32x32x16_bf16 v[34:49], v[212:215], v[8:11], v[34:49]
	v_mfma_f32_32x32x16_bf16 v[18:33], v[220:223], v[8:11], v[18:33]
	v_mfma_f32_32x32x16_bf16 v[66:81], v[12:15], v[146:149], v[66:81]
	v_mfma_f32_32x32x16_bf16 v[50:65], v[154:157], v[146:149], v[50:65]
	v_mfma_f32_32x32x16_bf16 v[34:49], v[216:219], v[146:149], v[34:49]
	v_mfma_f32_32x32x16_bf16 v[18:33], v[224:227], v[146:149], v[18:33]
	s_cbranch_scc0 .LBB0_584
	s_setprio 0
	s_nop 0
	v_and_b32_e32 v2, 63, v186
	s_cmpk_lt_u32 s56, 0x100
	s_cbranch_scc0 .LBB0_605
